# attention loops: scalar loop control and load guards, no wave-group stagger in diff loop
# baseline (speedup 1.0000x reference)
; DI int opaque_tid() { int t = threadIdx.x; asm volatile("" : "+v"(t)); return t; }
; DI void flash_pass_q2(f32x16 (&o)[2][2], const u16* __restrict__ Qp0, const u16* __restrict__ Qp1,
;                       const u16* __restrict__ Kb, int ldk, const u16* __restrict__ Vt, int S, int ntiles, char* lds) {
;   const int tid = opaque_tid(), lane = tid & 63;
;   const int h = lane >> 5, r = lane & 31;
;   bf16x8 q[2][4];
; #pragma unroll
;   for (int ks = 0; ks < 4; ++ks) {
;     q[0][ks] = *(const bf16x8*)(Qp0 + ks * 16 + h * 8);
;     q[1][ks] = *(const bf16x8*)(Qp1 + ks * 16 + h * 8);
;   }
; #pragma unroll
;   for (int hq = 0; hq < 2; ++hq)
; #pragma unroll
;     for (int mv = 0; mv < 2; ++mv)
; #pragma unroll
;       for (int i = 0; i < 16; ++i) o[hq][mv][i] = 0.f;
;   float m_run[2] = {-INFINITY, -INFINITY}, l_run[2] = {0.f, 0.f};
;   const int lr = tid >> 3, lc = tid & 7;
;   const int wsw = lr * 128 + ((lc ^ ((lr >> 1) & 7)) << 4);
;   u32x4 rk, rv;
;   auto gload = [&](int ti) {
;     const size_t key0 = (size_t)ti * 64;
;     rk = *(const u32x4*)(Kb + (key0 + lr) * ldk + lc * 8);
;     rv = *(const u32x4*)(Vt + (size_t)lr * S + key0 + lc * 8);
;   };
;   auto swrite = [&](int st) {
;     char* ks_ = lds + st * ATT_STAGE;
;     *(u32x4*)(ks_ + wsw) = rk;
;     *(u32x4*)(ks_ + 8192 + wsw) = rv;
;   };
;   const int pr = (r & 0x13) | ((r & 4) << 1) | ((r & 8) >> 1);
;   const int ksw = (pr >> 1) & 7;
;   const int vsw = (r >> 1) & 7;
;   __syncthreads();
;   gload(0);
;   swrite(0);
;   if (ntiles > 1) gload(1);
;   __syncthreads();
.LBB0_275:
	s_andn2_saveexec_b64 s[18:19], s[18:19]
	v_ashrrev_i32_e32 v2, 8, v0
	v_lshrrev_b32_e32 v8, 6, v0
	v_and_b32_e32 v3, 63, v0
	s_or_b64 s[16:17], s[16:17], exec
	s_or_b64 exec, exec, s[18:19]
	v_lshlrev_b32_e32 v0, 14, v2
	v_lshl_add_u32 v4, v2, 11, v220
	v_cmp_gt_i32_e32 vcc, 2, v2
	v_lshlrev_b32_e32 v2, 8, v3
	v_mov_b64_e32 v[10:11], s[2:3]
	v_cndmask_b32_e32 v0, v4, v0, vcc
	s_movk_i32 s20, 0x500
	v_add3_u32 v196, v226, v2, v0
	v_mad_i64_i32 v[2:3], s[18:19], v0, s96, 0
	v_mad_i64_i32 v[160:161], s[18:19], v0, s96, v[10:11]
	v_mad_i64_i32 v[4:5], s[18:19], v0, s20, 0
	v_readlane_b32 s18, v254, 1
	v_readlane_b32 s19, v254, 2
	v_and_b32_e32 v9, 3, v8
	v_cndmask_b32_e32 v12, v221, v222, vcc
	v_mov_b64_e32 v[6:7], s[18:19]
	s_xor_b64 s[16:17], s[16:17], -1
	v_mad_i64_i32 v[6:7], s[18:19], v0, s20, v[6:7]
	v_ashrrev_i32_e32 v197, 31, v196
	v_mad_i64_i32 v[162:163], s[18:19], v196, s96, v[10:11]
	v_lshlrev_b32_e32 v198, 7, v9
	v_lshrrev_b32_e32 v185, 6, v12
	s_waitcnt vmcnt(9)
	v_cndmask_b32_e64 v176, 11, 14, vcc
	s_and_saveexec_b64 s[18:19], s[16:17]
	s_xor_b64 s[16:17], exec, s[18:19]
	s_cbranch_execz .LBB0_291
	v_lshlrev_b32_e32 v0, 8, v9
	v_lshl_add_u64 v[10:11], v[162:163], 0, v[0:1]
	v_lshlrev_b32_e32 v0, 5, v9
	v_and_b32_e32 v9, 64, v0
	v_lshlrev_b32_e32 v0, 1, v9
	v_lshl_add_u64 v[12:13], v[160:161], 0, v[0:1]
	v_or_b32_e32 v0, 0x200, v9
	v_mov_b32_e32 v9, v204
	v_mov_b32_e32 v15, v1
	v_bfe_u32 v24, v9, 5, 1
	v_lshlrev_b32_e32 v14, 4, v24
	v_lshl_add_u64 v[10:11], v[10:11], 0, v[14:15]
	v_ashrrev_i32_e32 v18, 3, v9
	v_lshlrev_b32_e32 v25, 4, v9
	v_lshlrev_b32_e32 v0, v176, v0
	global_load_dwordx4 v[168:171], v[10:11], off offset:2048
	global_load_dwordx4 v[164:167], v[10:11], off offset:2080
	global_load_dwordx4 v[172:175], v[10:11], off offset:2176
	global_load_dwordx4 v[160:163], v[10:11], off offset:2208
	global_load_dwordx4 v[156:159], v[10:11], off offset:2112
	global_load_dwordx4 v[148:151], v[10:11], off offset:2144
	global_load_dwordx4 v[152:155], v[10:11], off offset:2240
	global_load_dwordx4 v[144:147], v[10:11], off offset:2272
	v_ashrrev_i32_e32 v19, 31, v18
	v_mad_i64_i32 v[10:11], s[18:19], v18, s96, v[12:13]
	v_and_b32_e32 v12, 0x70, v25
	v_mov_b32_e32 v13, v1
	v_lshlrev_b32_e32 v0, 1, v0
	v_lshl_add_u64 v[20:21], v[10:11], 0, v[12:13]
	v_lshlrev_b64 v[10:11], v176, v[18:19]
	v_lshl_add_u64 v[6:7], v[6:7], 0, v[0:1]
	v_lshlrev_b64 v[22:23], 1, v[10:11]
	v_lshl_add_u64 v[6:7], v[6:7], 0, v[22:23]
	s_barrier
	v_lshl_add_u64 v[6:7], v[6:7], 0, v[12:13]
	global_load_dwordx4 v[10:13], v[20:21], off offset:3072
	global_load_dwordx4 v[14:17], v[6:7], off
	v_add_co_u32_e32 v20, vcc, s97, v20
	v_lshlrev_b32_e32 v19, 1, v9
	s_nop 0
	v_addc_co_u32_e32 v21, vcc, 0, v21, vcc
	global_load_dwordx4 v[176:179], v[20:21], off offset:3072
	global_load_dwordx4 v[180:183], v[6:7], off offset:128
	v_lshrrev_b32_e32 v20, 1, v9
	v_and_b32_e32 v7, 19, v9
	v_and_b32_e32 v19, 8, v19
	v_and_b32_e32 v20, 4, v20
	v_lshrrev_b32_e32 v6, 5, v9
	v_bfe_u32 v21, v9, 1, 3
	v_lshlrev_b32_e32 v26, 7, v9
	v_and_b32_e32 v27, 7, v9
	v_lshlrev_b32_e32 v28, 7, v18
	v_xor_b32_e32 v9, v25, v9
	v_or3_b32 v7, v19, v7, v20
	v_and_or_b32 v237, v9, s66, v28
	v_lshrrev_b32_e32 v9, 1, v7
	v_lshlrev_b32_e32 v238, 7, v7
	v_bitop3_b32 v7, v9, v24, 7 bitop3:0x6c
	v_bitop3_b32 v30, v6, v21, 1 bitop3:0x6c
	v_lshlrev_b32_e32 v6, 4, v27
	v_lshlrev_b32_e32 v239, 4, v7
	v_mov_b32_e32 v7, v1
	v_lshl_add_u64 v[4:5], v[4:5], 0, v[6:7]
	v_lshl_add_u64 v[4:5], v[4:5], 0, v[22:23]
	v_readlane_b32 s18, v254, 45
	v_lshl_add_u64 v[4:5], v[4:5], 0, v[0:1]
	v_readlane_b32 s19, v254, 46
	v_and_b32_e32 v0, 2, v8
	v_lshlrev_b32_e32 v0, 6, v0
	v_lshl_add_u64 v[200:201], s[18:19], 0, v[4:5]
	v_mad_i64_i32 v[2:3], s[18:19], v18, s96, v[2:3]
	v_and_b32_e32 v195, 0xf80, v26
	v_or_b32_e32 v25, 2, v24
	v_or_b32_e32 v26, 4, v24
	v_or_b32_e32 v29, 6, v24
	v_lshl_add_u64 v[2:3], v[2:3], 0, v[0:1]
	v_readlane_b32 s18, v254, 47
	v_bitop3_b32 v31, v24, v21, 2 bitop3:0x36
	v_bitop3_b32 v32, v24, v21, 4 bitop3:0x36
	v_bitop3_b32 v21, v24, v21, 6 bitop3:0x36
	v_bitop3_b32 v19, v9, v25, 7 bitop3:0x6c
	v_bitop3_b32 v20, v9, v26, 7 bitop3:0x6c
	v_bitop3_b32 v9, v9, v29, 7 bitop3:0x6c
	v_lshl_add_u64 v[2:3], v[2:3], 0, v[6:7]
	v_readlane_b32 s19, v254, 48
	v_lshlrev_b32_e32 v232, 4, v30
	v_lshlrev_b32_e32 v231, 4, v31
	v_lshlrev_b32_e32 v230, 4, v32
	v_lshlrev_b32_e32 v228, 4, v21
	v_lshlrev_b32_e32 v236, 4, v19
	v_lshlrev_b32_e32 v235, 4, v20
	v_lshlrev_b32_e32 v234, 4, v9
	v_lshl_add_u64 v[202:203], s[18:19], 0, v[2:3]
	v_mov_b32_e32 v0, v1
	v_mov_b32_e32 v2, v1
	s_waitcnt vmcnt(3)
	ds_write_b128 v237, v[10:13]
	s_waitcnt vmcnt(2)
	ds_write_b128 v237, v[14:17] offset:8192
	v_mov_b32_e32 v14, v1
	v_mov_b32_e32 v15, v1
	v_mov_b32_e32 v3, v1
	v_mov_b32_e32 v4, v1
	v_mov_b32_e32 v5, v1
	v_mov_b32_e32 v6, v1
	v_mov_b32_e32 v8, v1
	v_mov_b32_e32 v9, v1
	v_mov_b32_e32 v10, v1
	v_mov_b32_e32 v11, v1
	v_mov_b32_e32 v12, v1
	v_mov_b32_e32 v13, v1
	v_mov_b64_e32 v[30:31], v[14:15]
	v_mov_b64_e32 v[46:47], v[14:15]
	v_mov_b64_e32 v[62:63], v[14:15]
	v_mov_b64_e32 v[78:79], v[14:15]
	s_mov_b32 s22, 1
	v_mov_b32_e32 v229, 0
	v_mov_b32_e32 v233, 0xff800000
	s_mov_b64 s[18:19], 0
	v_mov_b64_e32 v[28:29], v[12:13]
	v_mov_b64_e32 v[26:27], v[10:11]
	v_mov_b64_e32 v[24:25], v[8:9]
	v_mov_b64_e32 v[22:23], v[6:7]
	v_mov_b64_e32 v[20:21], v[4:5]
	v_mov_b64_e32 v[18:19], v[2:3]
	v_mov_b64_e32 v[16:17], v[0:1]
	v_mov_b64_e32 v[44:45], v[12:13]
	v_mov_b64_e32 v[42:43], v[10:11]
	v_mov_b64_e32 v[40:41], v[8:9]
	v_mov_b64_e32 v[38:39], v[6:7]
	v_mov_b64_e32 v[36:37], v[4:5]
	v_mov_b64_e32 v[34:35], v[2:3]
	v_mov_b64_e32 v[32:33], v[0:1]
	v_mov_b64_e32 v[60:61], v[12:13]
	v_mov_b64_e32 v[58:59], v[10:11]
	v_mov_b64_e32 v[56:57], v[8:9]
	v_mov_b64_e32 v[54:55], v[6:7]
	v_mov_b64_e32 v[52:53], v[4:5]
	v_mov_b64_e32 v[50:51], v[2:3]
	v_mov_b64_e32 v[48:49], v[0:1]
	v_mov_b64_e32 v[76:77], v[12:13]
	v_mov_b64_e32 v[74:75], v[10:11]
	v_mov_b64_e32 v[72:73], v[8:9]
	v_mov_b64_e32 v[70:71], v[6:7]
	v_mov_b64_e32 v[68:69], v[4:5]
	v_mov_b64_e32 v[66:67], v[2:3]
	v_mov_b64_e32 v[64:65], v[0:1]
	v_mov_b32_e32 v10, 0xff800000
	v_mov_b32_e32 v0, 0
	s_waitcnt lgkmcnt(0)
	s_barrier
	v_readfirstlane_b32 s100, v185
	s_branch .LBB0_280
; #define MFMA(a, b, c) __builtin_amdgcn_mfma_f32_32x32x16_bf16((a), (b), (c), 0, 0, 0)
; DI void flash_pass_q2(f32x16 (&o)[2][2], const u16* __restrict__ Qp0, const u16* __restrict__ Qp1,
;                       const u16* __restrict__ Kb, int ldk, const u16* __restrict__ Vt, int S, int ntiles, char* lds) {
;     ...
;   for (int ti = 0; ti < ntiles; ++ti) {
;     if (ti + 1 < ntiles) {
;       swrite((ti + 1) & 1);
;       if (ti + 2 < ntiles) gload(ti + 2);
;     }
;     const char* st = lds + (ti & 1) * ATT_STAGE;
;     f32x16 s[2][2];
; #pragma unroll
;     for (int hq = 0; hq < 2; ++hq)
; #pragma unroll
;       for (int kb = 0; kb < 2; ++kb)
; #pragma unroll
;         for (int i = 0; i < 16; ++i) s[hq][kb][i] = 0.f;
;     {
;       bf16x8 ka[4], kb_[4];
; #pragma unroll
;       for (int ks = 0; ks < 4; ++ks) {
;         const int co = ((2 * ks + h) ^ ksw) << 4;
;         ka[ks] = *(const bf16x8*)(st + pr * 128 + co);
;         kb_[ks] = *(const bf16x8*)(st + (32 + pr) * 128 + co);
;       }
;       asm volatile("" ::: "memory");
; #pragma unroll
;       for (int ks = 0; ks < 4; ++ks) {
;         s[0][0] = MFMA(ka[ks], q[0][ks], s[0][0]);
;         s[0][1] = MFMA(kb_[ks], q[0][ks], s[0][1]);
;         s[1][0] = MFMA(ka[ks], q[1][ks], s[1][0]);
;         s[1][1] = MFMA(kb_[ks], q[1][ks], s[1][1]);
;       }
.LBB0_280:
	s_and_b32 s29, 1, s22
	s_cselect_b32 s23, 0x6000, 0
	s_cselect_b32 s21, 0, 0x6000
	s_add_i32 s22, s22, 1
	v_add_u32_e32 v11, s21, v238
	v_add_u32_e32 v248, s21, v195
	v_add_u32_e32 v249, v11, v239
	ds_read_b128 v[2:5], v249
	ds_read_b128 v[6:9], v249 offset:4096
	v_add_u32_e32 v249, v11, v236
	ds_read_b128 v[12:15], v249
	ds_read_b128 v[240:243], v249 offset:4096
	v_add_u32_e32 v249, s23, v237
	s_waitcnt vmcnt(1)
	ds_write_b128 v249, v[176:179]
	s_waitcnt vmcnt(0)
	ds_write_b128 v249, v[180:183] offset:8192
	s_cmp_lt_u32 s22, s100
	s_cbranch_scc0 .Lg2_noload
	global_load_dwordx4 v[176:179], v[202:203], off
	global_load_dwordx4 v[180:183], v[200:201], off
	v_lshl_add_u64 v[200:201], v[200:201], 0, s[4:5]
	v_lshl_add_u64 v[202:203], v[202:203], 0, s[82:83]
.Lg2_noload:
	s_waitcnt lgkmcnt(5)
	v_mfma_f32_32x32x16_bf16 v[128:143], v[2:5], v[168:171], 0
	s_waitcnt lgkmcnt(4)
	v_mfma_f32_32x32x16_bf16 v[112:127], v[6:9], v[168:171], 0
	v_mfma_f32_32x32x16_bf16 v[96:111], v[2:5], v[172:175], 0
	v_mfma_f32_32x32x16_bf16 v[80:95], v[6:9], v[172:175], 0
	v_add_u32_e32 v249, v11, v235
	ds_read_b128 v[2:5], v249
	ds_read_b128 v[6:9], v249 offset:4096
	s_waitcnt lgkmcnt(5)
	v_mfma_f32_32x32x16_bf16 v[128:143], v[12:15], v[164:167], v[128:143]
	s_waitcnt lgkmcnt(4)
	v_mfma_f32_32x32x16_bf16 v[112:127], v[240:243], v[164:167], v[112:127]
	v_mfma_f32_32x32x16_bf16 v[96:111], v[12:15], v[160:163], v[96:111]
	v_mfma_f32_32x32x16_bf16 v[80:95], v[240:243], v[160:163], v[80:95]
	v_add_u32_e32 v249, v11, v234
	ds_read_b128 v[12:15], v249
	ds_read_b128 v[240:243], v249 offset:4096
	s_waitcnt lgkmcnt(3)
	v_mfma_f32_32x32x16_bf16 v[128:143], v[2:5], v[156:159], v[128:143]
	s_waitcnt lgkmcnt(2)
	v_mfma_f32_32x32x16_bf16 v[112:127], v[6:9], v[156:159], v[112:127]
	v_mfma_f32_32x32x16_bf16 v[96:111], v[2:5], v[152:155], v[96:111]
	v_mfma_f32_32x32x16_bf16 v[80:95], v[6:9], v[152:155], v[80:95]
	v_add_u32_e32 v249, v248, v232
	ds_read_b128 v[2:5], v249 offset:8192
	ds_read_b128 v[6:9], v249 offset:12288
	s_waitcnt lgkmcnt(3)
	v_mfma_f32_32x32x16_bf16 v[128:143], v[12:15], v[148:151], v[128:143]
	s_waitcnt lgkmcnt(2)
	v_mfma_f32_32x32x16_bf16 v[112:127], v[240:243], v[148:151], v[112:127]
	v_mfma_f32_32x32x16_bf16 v[96:111], v[12:15], v[144:147], v[96:111]
	v_mfma_f32_32x32x16_bf16 v[80:95], v[240:243], v[144:147], v[80:95]
	v_add_u32_e32 v249, v248, v231
	ds_read_b128 v[12:15], v249 offset:8192
	ds_read_b128 v[240:243], v249 offset:12288

; #define MFMA(a, b, c) __builtin_amdgcn_mfma_f32_32x32x16_bf16((a), (b), (c), 0, 0, 0)
; DI float fexp2(float x) { return __builtin_amdgcn_exp2f(x); }
; DI void flash_pass_q2(f32x16 (&o)[2][2], const u16* __restrict__ Qp0, const u16* __restrict__ Qp1,
;                       const u16* __restrict__ Kb, int ldk, const u16* __restrict__ Vt, int S, int ntiles, char* lds) {
;     ...
;       float ls = 0.f;
; #pragma unroll
;       for (int e = 0; e < 32; ++e) { t[e] = fexp2(t[e] - m_run[hq]); ls += t[e]; }
;       l_run[hq] += ls;
; #pragma unroll
;       for (int kb = 0; kb < 2; ++kb)
; #pragma unroll
;         for (int c2 = 0; c2 < 2; ++c2) {
;           const int e0 = kb * 16 + c2 * 8;
;           u32x4 pw = {pk_bf16(t[e0], t[e0 + 1]), pk_bf16(t[e0 + 2], t[e0 + 3]), pk_bf16(t[e0 + 4], t[e0 + 5]), pk_bf16(t[e0 + 6], t[e0 + 7])};
;           pf[hq][kb][c2] = __builtin_bit_cast(bf16x8, pw);
;         }
;     }
;     bf16x8 vf[2][2][2];
; #pragma unroll
;     for (int kb = 0; kb < 2; ++kb)
; #pragma unroll
;       for (int c2 = 0; c2 < 2; ++c2) {
;         const int co = ((4 * kb + 2 * c2 + h) ^ vsw) << 4;
; #pragma unroll
;         for (int mv = 0; mv < 2; ++mv) vf[kb][c2][mv] = *(const bf16x8*)(st + 8192 + (mv * 32 + r) * 128 + co);
;       }
;     asm volatile("" ::: "memory");
; #pragma unroll
;     for (int kb = 0; kb < 2; ++kb)
; #pragma unroll
;       for (int c2 = 0; c2 < 2; ++c2)
; #pragma unroll
;         for (int mv = 0; mv < 2; ++mv) {
;           o[0][mv] = MFMA(vf[kb][c2][mv], pf[0][kb][c2], o[0][mv]);
;           o[1][mv] = MFMA(vf[kb][c2][mv], pf[1][kb][c2], o[1][mv]);
;         }
;     __syncthreads();
;   }
.Lg2_sm1:
	v_sub_f32_e32 v96, v96, v233
	v_sub_f32_e32 v97, v97, v233
	v_sub_f32_e32 v98, v98, v233
	v_sub_f32_e32 v99, v99, v233
	v_sub_f32_e32 v100, v100, v233
	v_sub_f32_e32 v101, v101, v233
	v_sub_f32_e32 v102, v102, v233
	v_sub_f32_e32 v103, v103, v233
	v_sub_f32_e32 v104, v104, v233
	v_sub_f32_e32 v105, v105, v233
	v_sub_f32_e32 v106, v106, v233
	v_sub_f32_e32 v107, v107, v233
	v_sub_f32_e32 v108, v108, v233
	v_sub_f32_e32 v109, v109, v233
	v_sub_f32_e32 v110, v110, v233
	v_sub_f32_e32 v111, v111, v233
	v_sub_f32_e32 v80, v80, v233
	v_sub_f32_e32 v81, v81, v233
	v_sub_f32_e32 v82, v82, v233
	v_sub_f32_e32 v83, v83, v233
	v_sub_f32_e32 v84, v84, v233
	v_sub_f32_e32 v85, v85, v233
	v_sub_f32_e32 v86, v86, v233
	v_sub_f32_e32 v87, v87, v233
	v_sub_f32_e32 v88, v88, v233
	v_sub_f32_e32 v89, v89, v233
	v_sub_f32_e32 v90, v90, v233
	v_sub_f32_e32 v91, v91, v233
	v_sub_f32_e32 v92, v92, v233
	v_sub_f32_e32 v93, v93, v233
	v_sub_f32_e32 v94, v94, v233
	v_sub_f32_e32 v95, v95, v233
	v_exp_f32_e32 v96, v96
	v_exp_f32_e32 v97, v97
	v_exp_f32_e32 v98, v98
	v_exp_f32_e32 v99, v99
	v_exp_f32_e32 v100, v100
	v_exp_f32_e32 v101, v101
	v_exp_f32_e32 v102, v102
	v_exp_f32_e32 v103, v103
	v_exp_f32_e32 v104, v104
	v_exp_f32_e32 v105, v105
	v_add_f32_e32 v210, v96, v98
	v_add_f32_e32 v246, v97, v99
	v_exp_f32_e32 v106, v106
	v_exp_f32_e32 v107, v107
	v_add_f32_e32 v210, v210, v100
	v_add_f32_e32 v246, v246, v101
	v_exp_f32_e32 v108, v108
	v_exp_f32_e32 v109, v109
	v_add_f32_e32 v210, v210, v102
	v_add_f32_e32 v246, v246, v103
	v_exp_f32_e32 v110, v110
	v_exp_f32_e32 v111, v111
	v_add_f32_e32 v210, v210, v104
	v_add_f32_e32 v246, v246, v105
	v_exp_f32_e32 v80, v80
	v_exp_f32_e32 v81, v81
	v_add_f32_e32 v210, v210, v106
	v_add_f32_e32 v246, v246, v107
	v_exp_f32_e32 v82, v82
	v_exp_f32_e32 v83, v83
	v_add_f32_e32 v210, v210, v108
	v_add_f32_e32 v246, v246, v109
	v_exp_f32_e32 v84, v84
	v_exp_f32_e32 v85, v85
	v_add_f32_e32 v210, v210, v110
	v_add_f32_e32 v246, v246, v111
	v_exp_f32_e32 v86, v86
	v_exp_f32_e32 v87, v87
	v_add_f32_e32 v210, v210, v80
	v_add_f32_e32 v246, v246, v81
	v_exp_f32_e32 v88, v88
	v_exp_f32_e32 v89, v89
	v_add_f32_e32 v210, v210, v82
	v_add_f32_e32 v246, v246, v83
	v_exp_f32_e32 v90, v90
	v_exp_f32_e32 v91, v91
	v_add_f32_e32 v210, v210, v84
	v_add_f32_e32 v246, v246, v85
	v_exp_f32_e32 v92, v92
	v_exp_f32_e32 v93, v93
	v_add_f32_e32 v210, v210, v86
	v_add_f32_e32 v246, v246, v87
	v_exp_f32_e32 v94, v94
	v_exp_f32_e32 v95, v95
	v_add_f32_e32 v210, v210, v88
	v_add_f32_e32 v246, v246, v89
	v_add_f32_e32 v210, v210, v90
	v_add_f32_e32 v246, v246, v91
	v_add_f32_e32 v210, v210, v92
	v_add_f32_e32 v246, v246, v93
	v_add_f32_e32 v210, v210, v94
	v_add_f32_e32 v246, v246, v95
	v_add_f32_e32 v210, v210, v246
	v_cmp_lt_f32_e32 vcc, 0x5d800000, v210
	s_cbranch_vccnz .Lg2_fix1
	v_add_f32_e32 v229, v229, v210
	v_cvt_pk_bf16_f32 v96, v96, v97
	v_cvt_pk_bf16_f32 v97, v98, v99
	v_cvt_pk_bf16_f32 v98, v100, v101
	v_cvt_pk_bf16_f32 v99, v102, v103
	v_cvt_pk_bf16_f32 v104, v104, v105
	v_cvt_pk_bf16_f32 v105, v106, v107
	v_cvt_pk_bf16_f32 v106, v108, v109
	v_cvt_pk_bf16_f32 v107, v110, v111
	v_cvt_pk_bf16_f32 v80, v80, v81
	v_cvt_pk_bf16_f32 v81, v82, v83
	v_cvt_pk_bf16_f32 v82, v84, v85
	v_cvt_pk_bf16_f32 v83, v86, v87
	v_cvt_pk_bf16_f32 v88, v88, v89
	v_cvt_pk_bf16_f32 v89, v90, v91
	v_cvt_pk_bf16_f32 v90, v92, v93
	v_cvt_pk_bf16_f32 v91, v94, v95
	v_mfma_f32_32x32x16_bf16 v[32:47], v[2:5], v[96:99], v[32:47]
	v_mfma_f32_32x32x16_bf16 v[16:31], v[6:9], v[96:99], v[16:31]
	v_add_u32_e32 v249, v248, v230
	ds_read_b128 v[2:5], v249 offset:8192
	ds_read_b128 v[6:9], v249 offset:12288
	v_mfma_f32_32x32x16_bf16 v[32:47], v[12:15], v[104:107], v[32:47]
	v_mfma_f32_32x32x16_bf16 v[16:31], v[240:243], v[104:107], v[16:31]
	v_add_u32_e32 v249, v248, v228
	ds_read_b128 v[12:15], v249 offset:8192
	ds_read_b128 v[240:243], v249 offset:12288
	s_waitcnt lgkmcnt(3)
	v_mfma_f32_32x32x16_bf16 v[64:79], v[2:5], v[112:115], v[64:79]
	s_waitcnt lgkmcnt(2)
	v_mfma_f32_32x32x16_bf16 v[48:63], v[6:9], v[112:115], v[48:63]
	v_mfma_f32_32x32x16_bf16 v[32:47], v[2:5], v[80:83], v[32:47]
	v_mfma_f32_32x32x16_bf16 v[16:31], v[6:9], v[80:83], v[16:31]
	s_waitcnt lgkmcnt(1)
	v_mfma_f32_32x32x16_bf16 v[64:79], v[12:15], v[120:123], v[64:79]
	s_waitcnt lgkmcnt(0)
	v_mfma_f32_32x32x16_bf16 v[48:63], v[240:243], v[120:123], v[48:63]
	v_mfma_f32_32x32x16_bf16 v[32:47], v[12:15], v[88:91], v[32:47]
	v_mfma_f32_32x32x16_bf16 v[16:31], v[240:243], v[88:91], v[16:31]
	s_waitcnt lgkmcnt(0)
	s_barrier
	s_cmp_eq_u32 s22, s100
	s_cbranch_scc0 .LBB0_280
	v_mov_b32_e32 v14, s23
	s_branch .LBB0_286
; DI float fexp2(float x) { return __builtin_amdgcn_exp2f(x); }
; DI void flash_pass_q2(f32x16 (&o)[2][2], const u16* __restrict__ Qp0, const u16* __restrict__ Qp1,
;                       const u16* __restrict__ Kb, int ldk, const u16* __restrict__ Vt, int S, int ntiles, char* lds) {
;     ...
;       float mx = t[0];
; #pragma unroll
;       for (int e = 1; e < 32; ++e) mx = fmaxf(mx, t[e]);
;       mx = fmaxf(mx, __shfl_xor(mx, 32));
;       if (__builtin_amdgcn_ballot_w64(mx > m_run[hq] + 8.f) != 0ull) {
;         const float m_new = fmaxf(m_run[hq], mx);
;         const float alpha = fexp2(m_run[hq] - m_new);
;         l_run[hq] *= alpha;
;         m_run[hq] = m_new;
; #pragma unroll
;         for (int mv = 0; mv < 2; ++mv)
; #pragma unroll
;           for (int i = 0; i < 16; ++i) o[hq][mv][i] *= alpha;
;       }
.Lg2_fix0:
	s_waitcnt lgkmcnt(0)
	v_add_u32_e32 v11, s21, v238
	v_add_u32_e32 v249, v11, v239
	ds_read_b128 v[2:5], v249
	ds_read_b128 v[6:9], v249 offset:4096
	v_add_u32_e32 v249, v11, v236
	ds_read_b128 v[12:15], v249
	ds_read_b128 v[240:243], v249 offset:4096
	s_waitcnt lgkmcnt(3)
	v_mfma_f32_32x32x16_bf16 v[128:143], v[2:5], v[168:171], 0
	s_waitcnt lgkmcnt(2)
	v_mfma_f32_32x32x16_bf16 v[112:127], v[6:9], v[168:171], 0
	v_add_u32_e32 v249, v11, v235
	ds_read_b128 v[2:5], v249
	ds_read_b128 v[6:9], v249 offset:4096
	s_waitcnt lgkmcnt(3)
	v_mfma_f32_32x32x16_bf16 v[128:143], v[12:15], v[164:167], v[128:143]
	s_waitcnt lgkmcnt(2)
	v_mfma_f32_32x32x16_bf16 v[112:127], v[240:243], v[164:167], v[112:127]
	v_add_u32_e32 v249, v11, v234
	ds_read_b128 v[12:15], v249
	ds_read_b128 v[240:243], v249 offset:4096
	s_waitcnt lgkmcnt(3)
	v_mfma_f32_32x32x16_bf16 v[128:143], v[2:5], v[156:159], v[128:143]
	s_waitcnt lgkmcnt(2)
	v_mfma_f32_32x32x16_bf16 v[112:127], v[6:9], v[156:159], v[112:127]
	s_waitcnt lgkmcnt(1)
	v_mfma_f32_32x32x16_bf16 v[128:143], v[12:15], v[148:151], v[128:143]
	s_waitcnt lgkmcnt(0)
	v_mfma_f32_32x32x16_bf16 v[112:127], v[240:243], v[148:151], v[112:127]
	v_add_u32_e32 v249, v248, v232
	ds_read_b128 v[2:5], v249 offset:8192
	ds_read_b128 v[6:9], v249 offset:12288
	v_add_u32_e32 v249, v248, v231
	ds_read_b128 v[12:15], v249 offset:8192
	ds_read_b128 v[240:243], v249 offset:12288
	s_nop 3
	v_max3_f32 v244, v128, v129, v130
	v_max3_f32 v245, v139, v140, v141
	v_max3_f32 v247, v118, v119, v120
	v_max3_f32 v244, v244, v131, v132
	v_max3_f32 v245, v245, v142, v143
	v_max3_f32 v247, v247, v121, v122
	v_max3_f32 v244, v244, v133, v134
	v_max3_f32 v245, v245, v112, v113
	v_max3_f32 v247, v247, v123, v124
	v_max3_f32 v244, v244, v135, v136
	v_max3_f32 v245, v245, v114, v115
	v_max3_f32 v247, v247, v125, v126
	v_max3_f32 v244, v244, v137, v138
	v_max3_f32 v245, v245, v116, v117
	v_max_f32_e32 v247, v247, v127
	v_max3_f32 v244, v244, v245, v247
	v_mov_b32_e32 v245, v244
	v_max_f32_e32 v247, v10, v10
	s_nop 0
	v_permlane32_swap_b32_e32 v244, v245
	v_max3_f32 v245, v244, v245, v247
	v_sub_f32_e32 v247, v10, v245
	v_exp_f32_e32 v247, v247
	v_mov_b32_e32 v10, v245
	v_mov_b32_e32 v244, v247
	v_mul_f32_e32 v0, v0, v244
	v_pk_mul_f32 v[64:65], v[64:65], v[244:245] op_sel_hi:[1,0]
	v_pk_mul_f32 v[66:67], v[66:67], v[244:245] op_sel_hi:[1,0]
	v_pk_mul_f32 v[68:69], v[68:69], v[244:245] op_sel_hi:[1,0]
	v_pk_mul_f32 v[70:71], v[70:71], v[244:245] op_sel_hi:[1,0]
	v_pk_mul_f32 v[72:73], v[72:73], v[244:245] op_sel_hi:[1,0]
	v_pk_mul_f32 v[74:75], v[74:75], v[244:245] op_sel_hi:[1,0]
	v_pk_mul_f32 v[76:77], v[76:77], v[244:245] op_sel_hi:[1,0]
	v_pk_mul_f32 v[78:79], v[78:79], v[244:245] op_sel_hi:[1,0]
	v_pk_mul_f32 v[48:49], v[48:49], v[244:245] op_sel_hi:[1,0]
	v_pk_mul_f32 v[50:51], v[50:51], v[244:245] op_sel_hi:[1,0]
	v_pk_mul_f32 v[52:53], v[52:53], v[244:245] op_sel_hi:[1,0]
	v_pk_mul_f32 v[54:55], v[54:55], v[244:245] op_sel_hi:[1,0]
	v_pk_mul_f32 v[56:57], v[56:57], v[244:245] op_sel_hi:[1,0]
	v_pk_mul_f32 v[58:59], v[58:59], v[244:245] op_sel_hi:[1,0]
	v_pk_mul_f32 v[60:61], v[60:61], v[244:245] op_sel_hi:[1,0]
	v_pk_mul_f32 v[62:63], v[62:63], v[244:245] op_sel_hi:[1,0]
	s_branch .Lg2_sm0
.Lg2_fix1:
	s_waitcnt lgkmcnt(0)
	v_add_u32_e32 v11, s21, v238
	v_add_u32_e32 v249, v11, v239
	ds_read_b128 v[2:5], v249
	ds_read_b128 v[6:9], v249 offset:4096
	v_add_u32_e32 v249, v11, v236
	ds_read_b128 v[12:15], v249
	ds_read_b128 v[240:243], v249 offset:4096
	s_waitcnt lgkmcnt(3)
	v_mfma_f32_32x32x16_bf16 v[96:111], v[2:5], v[172:175], 0
	s_waitcnt lgkmcnt(2)
	v_mfma_f32_32x32x16_bf16 v[80:95], v[6:9], v[172:175], 0
	v_add_u32_e32 v249, v11, v235
	ds_read_b128 v[2:5], v249
	ds_read_b128 v[6:9], v249 offset:4096
	s_waitcnt lgkmcnt(3)
	v_mfma_f32_32x32x16_bf16 v[96:111], v[12:15], v[160:163], v[96:111]
	s_waitcnt lgkmcnt(2)
	v_mfma_f32_32x32x16_bf16 v[80:95], v[240:243], v[160:163], v[80:95]
	v_add_u32_e32 v249, v11, v234
	ds_read_b128 v[12:15], v249
	ds_read_b128 v[240:243], v249 offset:4096
	s_waitcnt lgkmcnt(3)
	v_mfma_f32_32x32x16_bf16 v[96:111], v[2:5], v[152:155], v[96:111]
	s_waitcnt lgkmcnt(2)
	v_mfma_f32_32x32x16_bf16 v[80:95], v[6:9], v[152:155], v[80:95]
	s_waitcnt lgkmcnt(1)
	v_mfma_f32_32x32x16_bf16 v[96:111], v[12:15], v[144:147], v[96:111]
	s_waitcnt lgkmcnt(0)
	v_mfma_f32_32x32x16_bf16 v[80:95], v[240:243], v[144:147], v[80:95]
	v_add_u32_e32 v249, v248, v232
	ds_read_b128 v[2:5], v249 offset:8192
	ds_read_b128 v[6:9], v249 offset:12288
	v_add_u32_e32 v249, v248, v231
	ds_read_b128 v[12:15], v249 offset:8192
	ds_read_b128 v[240:243], v249 offset:12288
	s_nop 3
	v_max3_f32 v244, v96, v97, v98
	v_max3_f32 v245, v107, v108, v109
	v_max3_f32 v247, v86, v87, v88
	v_max3_f32 v244, v244, v99, v100
	v_max3_f32 v245, v245, v110, v111
	v_max3_f32 v247, v247, v89, v90
	v_max3_f32 v244, v244, v101, v102
	v_max3_f32 v245, v245, v80, v81
	v_max3_f32 v247, v247, v91, v92
	v_max3_f32 v244, v244, v103, v104
	v_max3_f32 v245, v245, v82, v83
	v_max3_f32 v247, v247, v93, v94
	v_max3_f32 v244, v244, v105, v106
	v_max3_f32 v245, v245, v84, v85
	v_max_f32_e32 v247, v247, v95
	v_max3_f32 v244, v244, v245, v247
	v_mov_b32_e32 v245, v244
	v_max_f32_e32 v247, v233, v233
	s_nop 0
	v_permlane32_swap_b32_e32 v244, v245
	v_max3_f32 v245, v244, v245, v247
	v_sub_f32_e32 v247, v233, v245
	v_exp_f32_e32 v247, v247
	v_mov_b32_e32 v233, v245
	v_mov_b32_e32 v244, v247
	v_mul_f32_e32 v229, v229, v244
	v_pk_mul_f32 v[32:33], v[32:33], v[244:245] op_sel_hi:[1,0]
	v_pk_mul_f32 v[34:35], v[34:35], v[244:245] op_sel_hi:[1,0]
	v_pk_mul_f32 v[36:37], v[36:37], v[244:245] op_sel_hi:[1,0]
	v_pk_mul_f32 v[38:39], v[38:39], v[244:245] op_sel_hi:[1,0]
	v_pk_mul_f32 v[40:41], v[40:41], v[244:245] op_sel_hi:[1,0]
	v_pk_mul_f32 v[42:43], v[42:43], v[244:245] op_sel_hi:[1,0]
	v_pk_mul_f32 v[44:45], v[44:45], v[244:245] op_sel_hi:[1,0]
	v_pk_mul_f32 v[46:47], v[46:47], v[244:245] op_sel_hi:[1,0]
	v_pk_mul_f32 v[16:17], v[16:17], v[244:245] op_sel_hi:[1,0]
	v_pk_mul_f32 v[18:19], v[18:19], v[244:245] op_sel_hi:[1,0]
	v_pk_mul_f32 v[20:21], v[20:21], v[244:245] op_sel_hi:[1,0]
	v_pk_mul_f32 v[22:23], v[22:23], v[244:245] op_sel_hi:[1,0]
	v_pk_mul_f32 v[24:25], v[24:25], v[244:245] op_sel_hi:[1,0]
	v_pk_mul_f32 v[26:27], v[26:27], v[244:245] op_sel_hi:[1,0]
	v_pk_mul_f32 v[28:29], v[28:29], v[244:245] op_sel_hi:[1,0]
	v_pk_mul_f32 v[30:31], v[30:31], v[244:245] op_sel_hi:[1,0]
	s_branch .Lg2_sm1

; DI int opaque_tid() { int t = threadIdx.x; asm volatile("" : "+v"(t)); return t; }
; template <int DV, bool NA> ...
;   const int tid = opaque_tid(), lane = tid & 63;
;   const int h = lane >> 5, r = lane & 31;
;   bf16x8 q[4];
; #pragma unroll
;   for (int ks = 0; ks < 4; ++ks) q[ks] = *(const bf16x8*)(Qp + ks * 16 + h * 8);
; #pragma unroll
;   for (int mv = 0; mv < DV / 32; ++mv)
; #pragma unroll
;     for (int i = 0; i < 16; ++i) o[mv][i] = 0.f;
;   float m_run = -INFINITY, l_run = 0.f;
;   const int lr = tid >> 3, lc = tid & 7;
;   const int wsw = lr * 128 + ((lc ^ ((lr >> 1) & 7)) << 4);
;   u32x4 rk, rv[DV / 64];
;   auto gload = [&](int ti) {
;     const size_t key0 = (size_t)(tile0 + ti) * 64;
;     rk = *(const u32x4*)(Kb + (key0 + lr) * ldk + lc * 8);
; #pragma unroll
;     for (int i = 0; i < DV / 64; ++i) rv[i] = *(const u32x4*)(Vt + (size_t)(lr + 64 * i) * S + key0 + lc * 8);
;   };
;   auto swrite = [&](int st) {
;     char* ks_ = lds + st * ATT_STAGE;
;     *(u32x4*)(ks_ + wsw) = rk;
; #pragma unroll
;     for (int i = 0; i < DV / 64; ++i) *(u32x4*)(ks_ + 8192 + i * 8192 + wsw) = rv[i];
;   };
;   const int pr = (r & 0x13) | ((r & 4) << 1) | ((r & 8) >> 1);
;   const int ksw = (pr >> 1) & 7;
;   const int vsw = (r >> 1) & 7;
;   const int cs_ = NA ? min(max(qc - 8, 0), 48) : 0;
;   __syncthreads();
;   gload(0);
;   swrite(0);
;   if (ntiles > 1) gload(1);
;   __syncthreads();
; #pragma unroll 2
;   for (int ti = 0; ti < ntiles; ++ti) {
;     if (ti + 1 < ntiles) {
;       swrite((ti + 1) & 1);
;       if (ti + 2 < ntiles) gload(ti + 2);
.LBB0_294:
	v_or_b32_e32 v0, s20, v198
	v_mov_b32_e32 v26, v204
	v_lshlrev_b64 v[2:3], 1, v[0:1]
	v_lshl_add_u64 v[4:5], v[162:163], 0, v[2:3]
	v_bfe_u32 v27, v26, 5, 1
	v_lshl_add_u64 v[2:3], v[160:161], 0, v[2:3]
	v_lshlrev_b32_e32 v0, 4, v27
	v_ashrrev_i32_e32 v14, 3, v26
	v_lshlrev_b32_e32 v28, 4, v26
	v_lshl_add_u64 v[4:5], v[4:5], 0, v[0:1]
	v_ashrrev_i32_e32 v15, 31, v14
	v_mad_i64_i32 v[2:3], s[22:23], v14, s96, v[2:3]
	v_and_b32_e32 v0, 0x70, v28
	v_add_u32_e32 v10, 64, v14
	v_lshl_add_u64 v[16:17], v[2:3], 0, v[0:1]
	v_lshlrev_b64 v[2:3], v176, v[14:15]
	v_ashrrev_i32_e32 v11, 31, v10
	v_lshlrev_b64 v[18:19], 1, v[2:3]
	v_lshlrev_b64 v[10:11], v176, v[10:11]
	v_lshl_add_u64 v[2:3], v[164:165], 0, v[18:19]
	v_lshlrev_b64 v[22:23], 1, v[10:11]
	global_load_dwordx4 v[124:127], v[4:5], off
	global_load_dwordx4 v[120:123], v[4:5], off offset:32
	global_load_dwordx4 v[116:119], v[4:5], off offset:64
	global_load_dwordx4 v[112:115], v[4:5], off offset:96
	s_barrier
	v_lshl_add_u64 v[20:21], v[2:3], 0, v[0:1]
	global_load_dwordx4 v[2:5], v[16:17], off offset:1024
	global_load_dwordx4 v[6:9], v[20:21], off
	v_lshl_add_u64 v[10:11], v[164:165], 0, v[22:23]
	v_lshl_add_u64 v[24:25], v[10:11], 0, v[0:1]
	v_add_co_u32_e32 v16, vcc, s97, v16
	global_load_dwordx4 v[10:13], v[24:25], off
	s_nop 0
	v_addc_co_u32_e32 v17, vcc, 0, v17, vcc
	global_load_dwordx4 v[132:135], v[20:21], off offset:128
	global_load_dwordx4 v[128:131], v[16:17], off offset:1024
	global_load_dwordx4 v[136:139], v[24:25], off offset:128
	v_lshlrev_b32_e32 v15, 1, v26
	v_lshrrev_b32_e32 v20, 1, v26
	v_lshrrev_b32_e32 v16, 5, v26
	v_and_b32_e32 v17, 19, v26
	v_bfe_u32 v21, v26, 1, 3
	v_lshlrev_b32_e32 v24, 7, v26
	v_xor_b32_e32 v26, v28, v26
	v_and_b32_e32 v28, 8, v15
	v_and_b32_e32 v20, 4, v20
	v_bitop3_b32 v16, v16, v21, 1 bitop3:0x6c
	v_or3_b32 v17, v28, v17, v20
	v_lshlrev_b32_e32 v25, 7, v14
	v_and_b32_e32 v178, 0xf80, v24
	v_or_b32_e32 v24, 4, v27
	v_or_b32_e32 v29, 2, v27
	v_or_b32_e32 v30, 6, v27
	v_bitop3_b32 v31, v27, v21, 2 bitop3:0x36
	v_bitop3_b32 v32, v27, v21, 4 bitop3:0x36
	v_bitop3_b32 v21, v27, v21, 6 bitop3:0x36
	v_lshlrev_b32_e32 v195, 4, v16
	v_lshrrev_b32_e32 v16, 1, v17
	v_mad_i64_i32 v[14:15], s[22:23], v14, s96, 0
	v_and_or_b32 v203, v26, s66, v25
	v_lshlrev_b32_e32 v179, 4, v21
	v_lshlrev_b32_e32 v228, 7, v17
	v_bitop3_b32 v20, v16, v27, 7 bitop3:0x6c
	v_bitop3_b32 v21, v16, v29, 7 bitop3:0x6c
	v_bitop3_b32 v24, v16, v24, 7 bitop3:0x6c
	v_bitop3_b32 v25, v16, v30, 7 bitop3:0x6c
	v_lshl_add_u64 v[16:17], v[0:1], 0, v[18:19]
	v_or_b32_e32 v14, v14, v0
	v_lshl_add_u64 v[170:171], v[166:167], 0, v[16:17]
	v_lshl_add_u64 v[16:17], v[0:1], 0, v[22:23]
	v_add_u32_e32 v0, s20, v198
	s_waitcnt vmcnt(18)
	v_lshlrev_b32_e32 v183, 4, v31
	v_lshlrev_b32_e32 v181, 4, v32
	v_lshlrev_b32_e32 v229, 4, v20
	v_lshlrev_b32_e32 v202, 4, v21
	v_lshlrev_b32_e32 v201, 4, v24
	v_lshlrev_b32_e32 v200, 4, v25
	v_lshl_add_u64 v[172:173], v[166:167], 0, v[16:17]
	v_mov_b32_e32 v180, 0
	v_mov_b32_e32 v182, 0xff800000
	s_mov_b64 s[20:21], 0
	s_mov_b32 s31, 0
	s_waitcnt vmcnt(5)
	ds_write_b128 v203, v[2:5]
	s_waitcnt vmcnt(4)
	ds_write_b128 v203, v[6:9] offset:8192
	s_waitcnt vmcnt(3)
	ds_write_b128 v203, v[10:13] offset:16384
	v_lshl_add_u64 v[2:3], v[0:1], 1, v[14:15]
	v_mov_b32_e32 v14, v1
	v_mov_b32_e32 v15, v1
	v_lshl_add_u64 v[174:175], v[168:169], 0, v[2:3]
	v_mov_b32_e32 v0, v1
	v_mov_b32_e32 v2, v1
	v_mov_b32_e32 v3, v1
	v_mov_b32_e32 v4, v1
	v_mov_b32_e32 v5, v1
	v_mov_b32_e32 v6, v1
	v_mov_b32_e32 v7, v1
	v_mov_b32_e32 v8, v1
	v_mov_b32_e32 v9, v1
	v_mov_b32_e32 v10, v1
	v_mov_b32_e32 v11, v1
	v_mov_b32_e32 v12, v1
	v_mov_b32_e32 v13, v1
	v_mov_b64_e32 v[30:31], v[14:15]
	v_mov_b64_e32 v[46:47], v[14:15]
	v_mov_b64_e32 v[62:63], v[14:15]
	v_mov_b64_e32 v[78:79], v[14:15]
	v_mov_b64_e32 v[28:29], v[12:13]
	v_mov_b64_e32 v[26:27], v[10:11]
	v_mov_b64_e32 v[24:25], v[8:9]
	v_mov_b64_e32 v[22:23], v[6:7]
	v_mov_b64_e32 v[20:21], v[4:5]
	v_mov_b64_e32 v[18:19], v[2:3]
	v_mov_b64_e32 v[16:17], v[0:1]
	v_mov_b64_e32 v[44:45], v[12:13]
	v_mov_b64_e32 v[42:43], v[10:11]
	v_mov_b64_e32 v[40:41], v[8:9]
	v_mov_b64_e32 v[38:39], v[6:7]
	v_mov_b64_e32 v[36:37], v[4:5]
	v_mov_b64_e32 v[34:35], v[2:3]
	v_mov_b64_e32 v[32:33], v[0:1]
	v_mov_b64_e32 v[60:61], v[12:13]
	v_mov_b64_e32 v[58:59], v[10:11]
	v_mov_b64_e32 v[56:57], v[8:9]
	v_mov_b64_e32 v[54:55], v[6:7]
	v_mov_b64_e32 v[52:53], v[4:5]
	v_mov_b64_e32 v[50:51], v[2:3]
	v_mov_b64_e32 v[48:49], v[0:1]
	v_mov_b64_e32 v[76:77], v[12:13]
	v_mov_b64_e32 v[74:75], v[10:11]
	v_mov_b64_e32 v[72:73], v[8:9]
	v_mov_b64_e32 v[70:71], v[6:7]
	v_mov_b64_e32 v[68:69], v[4:5]
	v_mov_b64_e32 v[66:67], v[2:3]
	v_mov_b64_e32 v[64:65], v[0:1]
	v_mov_b32_e32 v182, 0
	s_mov_b32 s100, 0xff800000
	v_readfirstlane_b32 s101, v185
	v_mov_b32_e32 v234, 0
	v_mov_b32_e32 v235, 0
	v_mov_b32_e32 v236, 0
	v_mov_b32_e32 v237, 0
	v_mov_b32_e32 v238, 0
	v_mov_b32_e32 v239, 0
	v_mov_b32_e32 v240, 0
	v_mov_b32_e32 v241, 0
	v_mov_b32_e32 v242, 0
	v_mov_b32_e32 v243, 0
	v_mov_b32_e32 v244, 0
	v_mov_b32_e32 v245, 0
	v_mov_b32_e32 v246, 0
	v_mov_b32_e32 v247, 0
	v_mov_b32_e32 v248, 0
	v_mov_b32_e32 v249, 0
	s_add_i32 s23, s101, -1
	s_waitcnt lgkmcnt(0)
	s_barrier
	s_branch .LBB0_296
.LBB0_296:
	s_add_i32 s29, s31, 1
	s_bitcmp1_b32 s29, 0
	s_cselect_b32 s30, 0x6000, 0
	s_add_i32 s22, s31, 2
	v_add_u32_e32 v159, s30, v203
	s_waitcnt vmcnt(1)
	ds_write_b128 v159, v[128:131]
	ds_write_b128 v159, v[132:135] offset:8192
	s_waitcnt vmcnt(0)
	ds_write_b128 v159, v[136:139] offset:16384
	s_cmp_lt_u32 s22, s101
	s_cbranch_scc0 .Ldf_noload_t
	global_load_dwordx4 v[128:131], v[174:175], off
	global_load_dwordx4 v[132:135], v[170:171], off
	global_load_dwordx4 v[136:139], v[172:173], off
	v_lshl_add_u64 v[170:171], v[170:171], 0, s[4:5]
	v_lshl_add_u64 v[172:173], v[172:173], 0, s[4:5]
	v_lshl_add_u64 v[174:175], v[174:175], 0, s[82:83]
; #define MFMA(a, b, c) __builtin_amdgcn_mfma_f32_32x32x16_bf16((a), (b), (c), 0, 0, 0)
; DI float fexp2(float x) { return __builtin_amdgcn_exp2f(x); }
; template <int DV, bool NA> ...
;     ...
;       {
;         bf16x8 ka[4], kb_[4];
; #pragma unroll
;         for (int ks = 0; ks < 4; ++ks) {
;           const int co = ((2 * ks + h) ^ ksw) << 4;
;           ka[ks] = *(const bf16x8*)(st + pr * 128 + co);
;           kb_[ks] = *(const bf16x8*)(st + (32 + pr) * 128 + co);
;         }
;         asm volatile("" ::: "memory");
; #pragma unroll
;         for (int ks = 0; ks < 4; ++ks) {
;           s0 = MFMA(ka[ks], q[ks], s0);
;           s1 = MFMA(kb_[ks], q[ks], s1);
;         }
;       }
;       bf16x8 vf0[2][DV / 32];
; #pragma unroll
;       for (int c2 = 0; c2 < 2; ++c2) {
;         const int co = ((2 * c2 + h) ^ vsw) << 4;
; #pragma unroll
;         for (int mv = 0; mv < DV / 32; ++mv) vf0[c2][mv] = *(const bf16x8*)(st + 8192 + (mv * 32 + r) * 128 + co);
;     ...
;       float ls = 0.f;
; #pragma unroll
;       for (int e = 0; e < 32; ++e) { t[e] = fexp2(t[e] - m_run); ls += t[e]; }
;       l_run += ls;
;       bf16x8 pf[2][2];
; #pragma unroll
;       for (int kb = 0; kb < 2; ++kb)
; #pragma unroll
;         for (int c2 = 0; c2 < 2; ++c2) {
;           const int e0 = kb * 16 + c2 * 8;
;           u32x4 pw = {pk_bf16(t[e0], t[e0 + 1]), pk_bf16(t[e0 + 2], t[e0 + 3]), pk_bf16(t[e0 + 4], t[e0 + 5]), pk_bf16(t[e0 + 6], t[e0 + 7])};
;           pf[kb][c2] = __builtin_bit_cast(bf16x8, pw);
;         }
;       bf16x8 vf1[2][DV / 32];
; #pragma unroll
;       for (int c2 = 0; c2 < 2; ++c2) {
;         const int co = ((4 + 2 * c2 + h) ^ vsw) << 4;
; #pragma unroll
;         for (int mv = 0; mv < DV / 32; ++mv) vf1[c2][mv] = *(const bf16x8*)(st + 8192 + (mv * 32 + r) * 128 + co);
;       }
;       asm volatile("" ::: "memory");
; #pragma unroll
;       for (int c2 = 0; c2 < 2; ++c2)
; #pragma unroll
;         for (int mv = 0; mv < DV / 32; ++mv) o[mv] = MFMA(vf0[c2][mv], pf[0][c2], o[mv]);
; #pragma unroll
;       for (int c2 = 0; c2 < 2; ++c2)
; #pragma unroll
;         for (int mv = 0; mv < DV / 32; ++mv) o[mv] = MFMA(vf1[c2][mv], pf[1][c2], o[mv]);
;     }
;     __syncthreads();
.Ldf_noload_t:
	s_bitcmp1_b32 s31, 0
	s_cselect_b32 s22, 0x6000, 0
	v_add_u32_e32 v158, s22, v228
	v_add_u32_e32 v159, v158, v229
	ds_read_b128 v[0:3], v159
	ds_read_b128 v[4:7], v159 offset:4096
	v_add_u32_e32 v159, v158, v202
	ds_read_b128 v[8:11], v159
	ds_read_b128 v[12:15], v159 offset:4096
	v_add3_u32 v210, s22, v195, v178
	s_waitcnt lgkmcnt(3)
	v_mfma_f32_32x32x16_bf16 v[96:111], v[0:3], v[124:127], v[234:249]
	s_waitcnt lgkmcnt(2)
	v_mfma_f32_32x32x16_bf16 v[80:95], v[4:7], v[124:127], v[234:249]
	v_add_u32_e32 v159, v158, v201
	ds_read_b128 v[0:3], v159
	ds_read_b128 v[4:7], v159 offset:4096
	s_waitcnt lgkmcnt(3)
	v_mfma_f32_32x32x16_bf16 v[96:111], v[8:11], v[120:123], v[96:111]
	s_waitcnt lgkmcnt(2)
	v_mfma_f32_32x32x16_bf16 v[80:95], v[12:15], v[120:123], v[80:95]
	v_add_u32_e32 v159, v158, v200
	ds_read_b128 v[8:11], v159
	ds_read_b128 v[12:15], v159 offset:4096
	ds_read_b128 v[140:143], v210 offset:8192
	ds_read_b128 v[144:147], v210 offset:12288
	ds_read_b128 v[148:151], v210 offset:16384
	ds_read_b128 v[152:155], v210 offset:20480
	v_add3_u32 v230, s22, v183, v178
	s_waitcnt lgkmcnt(7)
	v_mfma_f32_32x32x16_bf16 v[96:111], v[0:3], v[116:119], v[96:111]
	s_waitcnt lgkmcnt(6)
	v_mfma_f32_32x32x16_bf16 v[80:95], v[4:7], v[116:119], v[80:95]
	s_waitcnt lgkmcnt(5)
	v_mfma_f32_32x32x16_bf16 v[96:111], v[8:11], v[112:115], v[96:111]
	s_waitcnt lgkmcnt(4)
	v_mfma_f32_32x32x16_bf16 v[80:95], v[12:15], v[112:115], v[80:95]
	ds_read_b128 v[0:3], v230 offset:8192
	ds_read_b128 v[4:7], v230 offset:12288
	ds_read_b128 v[8:11], v230 offset:16384
	ds_read_b128 v[12:15], v230 offset:20480
	v_add3_u32 v210, s22, v181, v178
	v_add3_u32 v230, s22, v179, v178
.Ldf_exps:
	s_nop 3
	v_exp_f32_e32 v96, v96
	v_exp_f32_e32 v97, v97
	v_exp_f32_e32 v98, v98
	v_exp_f32_e32 v99, v99
	v_exp_f32_e32 v100, v100
	v_exp_f32_e32 v101, v101
	v_exp_f32_e32 v102, v102
	v_exp_f32_e32 v103, v103
	v_exp_f32_e32 v104, v104
	v_exp_f32_e32 v105, v105
	v_add_f32_e32 v156, v96, v98
	v_add_f32_e32 v157, v97, v99
	v_exp_f32_e32 v106, v106
	v_exp_f32_e32 v107, v107
	v_add_f32_e32 v156, v156, v100
	v_add_f32_e32 v157, v157, v101
	v_exp_f32_e32 v108, v108
	v_exp_f32_e32 v109, v109
	v_add_f32_e32 v156, v156, v102
	v_add_f32_e32 v157, v157, v103
	v_exp_f32_e32 v110, v110
	v_exp_f32_e32 v111, v111
	v_add_f32_e32 v156, v156, v104
	v_add_f32_e32 v157, v157, v105
	v_exp_f32_e32 v80, v80
	v_exp_f32_e32 v81, v81
	v_add_f32_e32 v156, v156, v106
	v_add_f32_e32 v157, v157, v107
	v_exp_f32_e32 v82, v82
	v_exp_f32_e32 v83, v83
	v_add_f32_e32 v156, v156, v108
	v_add_f32_e32 v157, v157, v109
	v_exp_f32_e32 v84, v84
	v_exp_f32_e32 v85, v85
	v_add_f32_e32 v156, v156, v110
	v_add_f32_e32 v157, v157, v111
	v_exp_f32_e32 v86, v86
	v_exp_f32_e32 v87, v87
	v_add_f32_e32 v156, v156, v80
	v_add_f32_e32 v157, v157, v81
	v_exp_f32_e32 v88, v88
	v_exp_f32_e32 v89, v89
	v_add_f32_e32 v156, v156, v82
	v_add_f32_e32 v157, v157, v83
	v_exp_f32_e32 v90, v90
	v_exp_f32_e32 v91, v91
	v_add_f32_e32 v156, v156, v84
	v_add_f32_e32 v157, v157, v85
	v_exp_f32_e32 v92, v92
	v_exp_f32_e32 v93, v93
	v_add_f32_e32 v156, v156, v86
	v_add_f32_e32 v157, v157, v87
	v_exp_f32_e32 v94, v94
	v_exp_f32_e32 v95, v95
	v_add_f32_e32 v156, v156, v88
	v_add_f32_e32 v157, v157, v89
	v_add_f32_e32 v156, v156, v90
	v_add_f32_e32 v157, v157, v91
	v_add_f32_e32 v156, v156, v92
	v_add_f32_e32 v157, v157, v93
	v_add_f32_e32 v156, v156, v94
	v_add_f32_e32 v157, v157, v95
	v_add_f32_e32 v156, v156, v157
	v_cmp_lt_f32_e32 vcc, s100, v156
	s_cbranch_vccnz .Ldf_fix
	v_add_f32_e32 v180, v180, v156
	v_cvt_pk_bf16_f32 v96, v96, v97
	v_cvt_pk_bf16_f32 v97, v98, v99
	v_cvt_pk_bf16_f32 v98, v100, v101
	v_cvt_pk_bf16_f32 v99, v102, v103
	s_waitcnt lgkmcnt(7)
	s_nop 0
	v_mfma_f32_32x32x16_bf16 v[64:79], v[140:143], v[96:99], v[64:79]
	v_cvt_pk_bf16_f32 v104, v104, v105
	s_waitcnt lgkmcnt(6)
	v_mfma_f32_32x32x16_bf16 v[48:63], v[144:147], v[96:99], v[48:63]
	v_cvt_pk_bf16_f32 v105, v106, v107
	s_waitcnt lgkmcnt(5)
	v_mfma_f32_32x32x16_bf16 v[32:47], v[148:151], v[96:99], v[32:47]
	v_cvt_pk_bf16_f32 v106, v108, v109
	s_waitcnt lgkmcnt(4)
	v_mfma_f32_32x32x16_bf16 v[16:31], v[152:155], v[96:99], v[16:31]
	v_cvt_pk_bf16_f32 v107, v110, v111
	ds_read_b128 v[140:143], v210 offset:8192
	ds_read_b128 v[144:147], v210 offset:12288
	ds_read_b128 v[148:151], v210 offset:16384
	ds_read_b128 v[152:155], v210 offset:20480
	s_waitcnt lgkmcnt(7)
	v_mfma_f32_32x32x16_bf16 v[64:79], v[0:3], v[104:107], v[64:79]
	v_cvt_pk_bf16_f32 v80, v80, v81
	s_waitcnt lgkmcnt(6)
	v_mfma_f32_32x32x16_bf16 v[48:63], v[4:7], v[104:107], v[48:63]
	v_cvt_pk_bf16_f32 v81, v82, v83
	s_waitcnt lgkmcnt(5)
	v_mfma_f32_32x32x16_bf16 v[32:47], v[8:11], v[104:107], v[32:47]
	v_cvt_pk_bf16_f32 v82, v84, v85
	s_waitcnt lgkmcnt(4)
	v_mfma_f32_32x32x16_bf16 v[16:31], v[12:15], v[104:107], v[16:31]
	v_cvt_pk_bf16_f32 v83, v86, v87
	ds_read_b128 v[0:3], v230 offset:8192
	ds_read_b128 v[4:7], v230 offset:12288
	ds_read_b128 v[8:11], v230 offset:16384
	ds_read_b128 v[12:15], v230 offset:20480
	s_waitcnt lgkmcnt(7)
	v_mfma_f32_32x32x16_bf16 v[64:79], v[140:143], v[80:83], v[64:79]
	v_cvt_pk_bf16_f32 v88, v88, v89
	s_waitcnt lgkmcnt(6)
	v_mfma_f32_32x32x16_bf16 v[48:63], v[144:147], v[80:83], v[48:63]
	v_cvt_pk_bf16_f32 v89, v90, v91
	s_waitcnt lgkmcnt(5)
	v_mfma_f32_32x32x16_bf16 v[32:47], v[148:151], v[80:83], v[32:47]
	v_cvt_pk_bf16_f32 v90, v92, v93
	s_waitcnt lgkmcnt(4)
	v_mfma_f32_32x32x16_bf16 v[16:31], v[152:155], v[80:83], v[16:31]
	v_cvt_pk_bf16_f32 v91, v94, v95
	s_waitcnt lgkmcnt(3)
	s_nop 0
	v_mfma_f32_32x32x16_bf16 v[64:79], v[0:3], v[88:91], v[64:79]
	s_waitcnt lgkmcnt(2)
	v_mfma_f32_32x32x16_bf16 v[48:63], v[4:7], v[88:91], v[48:63]
	s_waitcnt lgkmcnt(1)
	v_mfma_f32_32x32x16_bf16 v[32:47], v[8:11], v[88:91], v[32:47]
	s_waitcnt lgkmcnt(0)
	v_mfma_f32_32x32x16_bf16 v[16:31], v[12:15], v[88:91], v[16:31]
	s_mov_b32 s31, s29
	s_waitcnt lgkmcnt(0)
	s_barrier
	s_cmp_eq_u32 s29, s23
	s_cbranch_scc0 .LBB0_296
	v_readfirstlane_b32 s101, v204
	v_mov_b32_e32 v0, s30
	v_mov_b32_e32 v1, 0
	s_lshr_b32 s101, s101, 8
	s_branch .LBB0_300
